# nt on phase 6's residual loads of the input x (read once), on top of the phase-0 and row-norm nt loads
# speedup vs baseline: 1.0041x; 1.0041x over previous
; #define PH(k) case k: if (ONLY_PHASE >= 0 && ONLY_PHASE != k) break;
; template <int ph> DI void run_phase(const Ctx& c, char* smem) {
;     ...
;     PH(6) gemm_phase(smem, (const bf16_t*)(ws + OFF_R1), 512, 512, (const bf16_t*)(ws + OFF_R2), 2592, (const bf16_t*)(ws + OFF_WABOUT), 1536, 8, EpiResid{p.x, p.out}, TIDX); break;
.Lg6_epi:
	s_nop 7
	s_nop 7
	s_lshl_b32 s20, s98, 12
	s_lshl_b32 s19, s21, 2
	s_add_u32 s20, s20, s19
	s_add_u32 s4, s6, s20
	s_addc_u32 s5, s7, 0
	s_lshl_b32 s20, s98, 12
	s_lshl_b32 s19, s21, 2
	s_add_u32 s20, s20, s19
	s_add_u32 s0, s14, s20
	s_addc_u32 s1, s15, 0
	ds_write_b128 v245, v[0:3]
	ds_write_b128 v245, v[4:7] offset:64
	ds_write_b128 v245, v[8:11] offset:128
	ds_write_b128 v245, v[12:15] offset:192
	ds_write_b128 v245, v[16:19] offset:4352
	ds_write_b128 v245, v[20:23] offset:4416
	ds_write_b128 v245, v[24:27] offset:4480
	ds_write_b128 v245, v[28:31] offset:4544
	ds_write_b128 v245, v[32:35] offset:8704
	ds_write_b128 v245, v[36:39] offset:8768
	ds_write_b128 v245, v[40:43] offset:8832
	ds_write_b128 v245, v[44:47] offset:8896
	ds_write_b128 v245, v[48:51] offset:13056
	ds_write_b128 v245, v[52:55] offset:13120
	ds_write_b128 v245, v[56:59] offset:13184
	ds_write_b128 v245, v[60:63] offset:13248
	global_load_dwordx4 v[128:131], v247, s[0:1] nt
	s_add_u32 s0, s0, 0x4000
	s_addc_u32 s1, s1, 0
	global_load_dwordx4 v[132:135], v247, s[0:1] nt
	s_add_u32 s0, s0, 0x4000
	s_addc_u32 s1, s1, 0
	global_load_dwordx4 v[136:139], v247, s[0:1] nt
	s_add_u32 s0, s0, 0x4000
	s_addc_u32 s1, s1, 0
	global_load_dwordx4 v[140:143], v247, s[0:1] nt
	s_add_u32 s0, s0, 0x4000
	s_addc_u32 s1, s1, 0
	global_load_dwordx4 v[144:147], v247, s[0:1] nt
	s_add_u32 s0, s0, 0x4000
	s_addc_u32 s1, s1, 0
	global_load_dwordx4 v[148:151], v247, s[0:1] nt
	s_add_u32 s0, s0, 0x4000
	s_addc_u32 s1, s1, 0
	global_load_dwordx4 v[152:155], v247, s[0:1] nt
	s_add_u32 s0, s0, 0x4000
	s_addc_u32 s1, s1, 0
	global_load_dwordx4 v[156:159], v247, s[0:1] nt
	s_add_u32 s0, s0, 0x4000
	s_addc_u32 s1, s1, 0
	s_waitcnt lgkmcnt(0)
	ds_read_b128 v[160:163], v246
	ds_read_b128 v[164:167], v246 offset:1088
	ds_read_b128 v[168:171], v246 offset:2176
	ds_read_b128 v[172:175], v246 offset:3264
	ds_read_b128 v[176:179], v246 offset:4352
	ds_read_b128 v[180:183], v246 offset:5440
	ds_read_b128 v[184:187], v246 offset:6528
	ds_read_b128 v[188:191], v246 offset:7616
	s_waitcnt vmcnt(7) lgkmcnt(7)
	v_pk_add_f32 v[128:129], v[128:129], v[160:161]
	v_pk_add_f32 v[130:131], v[130:131], v[162:163]
	global_store_dwordx4 v247, v[128:131], s[4:5] nt
	s_add_u32 s4, s4, 0x4000
	s_addc_u32 s5, s5, 0
	s_waitcnt vmcnt(7) lgkmcnt(6)
	v_pk_add_f32 v[132:133], v[132:133], v[164:165]
	v_pk_add_f32 v[134:135], v[134:135], v[166:167]
	global_store_dwordx4 v247, v[132:135], s[4:5] nt
	s_add_u32 s4, s4, 0x4000
	s_addc_u32 s5, s5, 0
	s_waitcnt vmcnt(7) lgkmcnt(5)
	v_pk_add_f32 v[136:137], v[136:137], v[168:169]
	v_pk_add_f32 v[138:139], v[138:139], v[170:171]
	global_store_dwordx4 v247, v[136:139], s[4:5] nt
	s_add_u32 s4, s4, 0x4000
	s_addc_u32 s5, s5, 0
	s_waitcnt vmcnt(7) lgkmcnt(4)
	v_pk_add_f32 v[140:141], v[140:141], v[172:173]
	v_pk_add_f32 v[142:143], v[142:143], v[174:175]
	global_store_dwordx4 v247, v[140:143], s[4:5] nt
	s_add_u32 s4, s4, 0x4000
	s_addc_u32 s5, s5, 0
	s_waitcnt vmcnt(7) lgkmcnt(3)
	v_pk_add_f32 v[144:145], v[144:145], v[176:177]
	v_pk_add_f32 v[146:147], v[146:147], v[178:179]
	global_store_dwordx4 v247, v[144:147], s[4:5] nt
	s_add_u32 s4, s4, 0x4000
	s_addc_u32 s5, s5, 0
	s_waitcnt vmcnt(7) lgkmcnt(2)
	v_pk_add_f32 v[148:149], v[148:149], v[180:181]
	v_pk_add_f32 v[150:151], v[150:151], v[182:183]
	global_store_dwordx4 v247, v[148:151], s[4:5] nt
	s_add_u32 s4, s4, 0x4000
	s_addc_u32 s5, s5, 0
	s_waitcnt vmcnt(7) lgkmcnt(1)
	v_pk_add_f32 v[152:153], v[152:153], v[184:185]
	v_pk_add_f32 v[154:155], v[154:155], v[186:187]
	global_store_dwordx4 v247, v[152:155], s[4:5] nt
	s_add_u32 s4, s4, 0x4000
	s_addc_u32 s5, s5, 0
	s_waitcnt vmcnt(7) lgkmcnt(0)
	v_pk_add_f32 v[156:157], v[156:157], v[188:189]
	v_pk_add_f32 v[158:159], v[158:159], v[190:191]
	global_store_dwordx4 v247, v[156:159], s[4:5] nt
	s_add_u32 s4, s4, 0x4000
	s_addc_u32 s5, s5, 0
	s_nop 1
	global_load_dwordx4 v[128:131], v247, s[0:1] nt
	s_add_u32 s0, s0, 0x4000
	s_addc_u32 s1, s1, 0
	global_load_dwordx4 v[132:135], v247, s[0:1] nt
	s_add_u32 s0, s0, 0x4000
	s_addc_u32 s1, s1, 0
	global_load_dwordx4 v[136:139], v247, s[0:1] nt
	s_add_u32 s0, s0, 0x4000
	s_addc_u32 s1, s1, 0
	global_load_dwordx4 v[140:143], v247, s[0:1] nt
	s_add_u32 s0, s0, 0x4000
	s_addc_u32 s1, s1, 0
	global_load_dwordx4 v[144:147], v247, s[0:1] nt
	s_add_u32 s0, s0, 0x4000
	s_addc_u32 s1, s1, 0
	global_load_dwordx4 v[148:151], v247, s[0:1] nt
	s_add_u32 s0, s0, 0x4000
	s_addc_u32 s1, s1, 0
	global_load_dwordx4 v[152:155], v247, s[0:1] nt
	s_add_u32 s0, s0, 0x4000
	s_addc_u32 s1, s1, 0
	global_load_dwordx4 v[156:159], v247, s[0:1] nt
	s_add_u32 s0, s0, 0x4000
	s_addc_u32 s1, s1, 0
	ds_read_b128 v[160:163], v246 offset:8704
	ds_read_b128 v[164:167], v246 offset:9792
	ds_read_b128 v[168:171], v246 offset:10880
	ds_read_b128 v[172:175], v246 offset:11968
	ds_read_b128 v[176:179], v246 offset:13056
	ds_read_b128 v[180:183], v246 offset:14144
	ds_read_b128 v[184:187], v246 offset:15232
	ds_read_b128 v[188:191], v246 offset:16320
	s_waitcnt vmcnt(7) lgkmcnt(7)
	v_pk_add_f32 v[128:129], v[128:129], v[160:161]
	v_pk_add_f32 v[130:131], v[130:131], v[162:163]
	global_store_dwordx4 v247, v[128:131], s[4:5] nt
	s_add_u32 s4, s4, 0x4000
	s_addc_u32 s5, s5, 0
	s_waitcnt vmcnt(7) lgkmcnt(6)
	v_pk_add_f32 v[132:133], v[132:133], v[164:165]
	v_pk_add_f32 v[134:135], v[134:135], v[166:167]
	global_store_dwordx4 v247, v[132:135], s[4:5] nt
	s_add_u32 s4, s4, 0x4000
	s_addc_u32 s5, s5, 0
	s_waitcnt vmcnt(7) lgkmcnt(5)
	v_pk_add_f32 v[136:137], v[136:137], v[168:169]
	v_pk_add_f32 v[138:139], v[138:139], v[170:171]
	global_store_dwordx4 v247, v[136:139], s[4:5] nt
	s_add_u32 s4, s4, 0x4000
	s_addc_u32 s5, s5, 0
	s_waitcnt vmcnt(7) lgkmcnt(4)
; #define PH(k) case k: if (ONLY_PHASE >= 0 && ONLY_PHASE != k) break;
; template <int ph> DI void run_phase(const Ctx& c, char* smem) {
;     ...
;     PH(6) gemm_phase(smem, (const bf16_t*)(ws + OFF_R1), 512, 512, (const bf16_t*)(ws + OFF_R2), 2592, (const bf16_t*)(ws + OFF_WABOUT), 1536, 8, EpiResid{p.x, p.out}, TIDX); break;
	v_pk_add_f32 v[140:141], v[140:141], v[172:173]
	v_pk_add_f32 v[142:143], v[142:143], v[174:175]
	global_store_dwordx4 v247, v[140:143], s[4:5] nt
	s_add_u32 s4, s4, 0x4000
	s_addc_u32 s5, s5, 0
	s_waitcnt vmcnt(7) lgkmcnt(3)
	v_pk_add_f32 v[144:145], v[144:145], v[176:177]
	v_pk_add_f32 v[146:147], v[146:147], v[178:179]
	global_store_dwordx4 v247, v[144:147], s[4:5] nt
	s_add_u32 s4, s4, 0x4000
	s_addc_u32 s5, s5, 0
	s_waitcnt vmcnt(7) lgkmcnt(2)
	v_pk_add_f32 v[148:149], v[148:149], v[180:181]
	v_pk_add_f32 v[150:151], v[150:151], v[182:183]
	global_store_dwordx4 v247, v[148:151], s[4:5] nt
	s_add_u32 s4, s4, 0x4000
	s_addc_u32 s5, s5, 0
	s_waitcnt vmcnt(7) lgkmcnt(1)
	v_pk_add_f32 v[152:153], v[152:153], v[184:185]
	v_pk_add_f32 v[154:155], v[154:155], v[186:187]
	global_store_dwordx4 v247, v[152:155], s[4:5] nt
	s_add_u32 s4, s4, 0x4000
	s_addc_u32 s5, s5, 0
	s_waitcnt vmcnt(7) lgkmcnt(0)
	v_pk_add_f32 v[156:157], v[156:157], v[188:189]
	v_pk_add_f32 v[158:159], v[158:159], v[190:191]
	global_store_dwordx4 v247, v[156:159], s[4:5] nt
	s_add_u32 s4, s4, 0x4000
	s_addc_u32 s5, s5, 0
	s_nop 1
	s_waitcnt lgkmcnt(0)
	ds_write_b128 v245, v[64:67]
	ds_write_b128 v245, v[68:71] offset:64
	ds_write_b128 v245, v[72:75] offset:128
	ds_write_b128 v245, v[76:79] offset:192
	ds_write_b128 v245, v[80:83] offset:4352
	ds_write_b128 v245, v[84:87] offset:4416
	ds_write_b128 v245, v[88:91] offset:4480
	ds_write_b128 v245, v[92:95] offset:4544
	ds_write_b128 v245, v[96:99] offset:8704
	ds_write_b128 v245, v[100:103] offset:8768
	ds_write_b128 v245, v[104:107] offset:8832
	ds_write_b128 v245, v[108:111] offset:8896
	ds_write_b128 v245, v[112:115] offset:13056
	ds_write_b128 v245, v[116:119] offset:13120
	ds_write_b128 v245, v[120:123] offset:13184
	ds_write_b128 v245, v[124:127] offset:13248
	global_load_dwordx4 v[128:131], v247, s[0:1] nt
	s_add_u32 s0, s0, 0x4000
	s_addc_u32 s1, s1, 0
	global_load_dwordx4 v[132:135], v247, s[0:1] nt
	s_add_u32 s0, s0, 0x4000
	s_addc_u32 s1, s1, 0
	global_load_dwordx4 v[136:139], v247, s[0:1] nt
	s_add_u32 s0, s0, 0x4000
	s_addc_u32 s1, s1, 0
	global_load_dwordx4 v[140:143], v247, s[0:1] nt
	s_add_u32 s0, s0, 0x4000
	s_addc_u32 s1, s1, 0
	global_load_dwordx4 v[144:147], v247, s[0:1] nt
	s_add_u32 s0, s0, 0x4000
	s_addc_u32 s1, s1, 0
	global_load_dwordx4 v[148:151], v247, s[0:1] nt
	s_add_u32 s0, s0, 0x4000
	s_addc_u32 s1, s1, 0
	global_load_dwordx4 v[152:155], v247, s[0:1] nt
	s_add_u32 s0, s0, 0x4000
	s_addc_u32 s1, s1, 0
	global_load_dwordx4 v[156:159], v247, s[0:1] nt
	s_add_u32 s0, s0, 0x4000
	s_addc_u32 s1, s1, 0
	s_waitcnt lgkmcnt(0)
	ds_read_b128 v[160:163], v246
	ds_read_b128 v[164:167], v246 offset:1088
	ds_read_b128 v[168:171], v246 offset:2176
	ds_read_b128 v[172:175], v246 offset:3264
	ds_read_b128 v[176:179], v246 offset:4352
	ds_read_b128 v[180:183], v246 offset:5440
	ds_read_b128 v[184:187], v246 offset:6528
	ds_read_b128 v[188:191], v246 offset:7616
	s_waitcnt vmcnt(7) lgkmcnt(7)
	v_pk_add_f32 v[128:129], v[128:129], v[160:161]
	v_pk_add_f32 v[130:131], v[130:131], v[162:163]
	global_store_dwordx4 v247, v[128:131], s[4:5] nt
	s_add_u32 s4, s4, 0x4000
	s_addc_u32 s5, s5, 0
	s_waitcnt vmcnt(7) lgkmcnt(6)
	v_pk_add_f32 v[132:133], v[132:133], v[164:165]
	v_pk_add_f32 v[134:135], v[134:135], v[166:167]
	global_store_dwordx4 v247, v[132:135], s[4:5] nt
	s_add_u32 s4, s4, 0x4000
	s_addc_u32 s5, s5, 0
	s_waitcnt vmcnt(7) lgkmcnt(5)
	v_pk_add_f32 v[136:137], v[136:137], v[168:169]
	v_pk_add_f32 v[138:139], v[138:139], v[170:171]
	global_store_dwordx4 v247, v[136:139], s[4:5] nt
	s_add_u32 s4, s4, 0x4000
	s_addc_u32 s5, s5, 0
	s_waitcnt vmcnt(7) lgkmcnt(4)
	v_pk_add_f32 v[140:141], v[140:141], v[172:173]
	v_pk_add_f32 v[142:143], v[142:143], v[174:175]
	global_store_dwordx4 v247, v[140:143], s[4:5] nt
	s_add_u32 s4, s4, 0x4000
	s_addc_u32 s5, s5, 0
	s_waitcnt vmcnt(7) lgkmcnt(3)
; #define PH(k) case k: if (ONLY_PHASE >= 0 && ONLY_PHASE != k) break;
; template <int ph> DI void run_phase(const Ctx& c, char* smem) {
;     ...
;     PH(6) gemm_phase(smem, (const bf16_t*)(ws + OFF_R1), 512, 512, (const bf16_t*)(ws + OFF_R2), 2592, (const bf16_t*)(ws + OFF_WABOUT), 1536, 8, EpiResid{p.x, p.out}, TIDX); break;
	v_pk_add_f32 v[144:145], v[144:145], v[176:177]
	v_pk_add_f32 v[146:147], v[146:147], v[178:179]
	global_store_dwordx4 v247, v[144:147], s[4:5] nt
	s_add_u32 s4, s4, 0x4000
	s_addc_u32 s5, s5, 0
	s_waitcnt vmcnt(7) lgkmcnt(2)
	v_pk_add_f32 v[148:149], v[148:149], v[180:181]
	v_pk_add_f32 v[150:151], v[150:151], v[182:183]
	global_store_dwordx4 v247, v[148:151], s[4:5] nt
	s_add_u32 s4, s4, 0x4000
	s_addc_u32 s5, s5, 0
	s_waitcnt vmcnt(7) lgkmcnt(1)
	v_pk_add_f32 v[152:153], v[152:153], v[184:185]
	v_pk_add_f32 v[154:155], v[154:155], v[186:187]
	global_store_dwordx4 v247, v[152:155], s[4:5] nt
	s_add_u32 s4, s4, 0x4000
	s_addc_u32 s5, s5, 0
	s_waitcnt vmcnt(7) lgkmcnt(0)
	v_pk_add_f32 v[156:157], v[156:157], v[188:189]
	v_pk_add_f32 v[158:159], v[158:159], v[190:191]
	global_store_dwordx4 v247, v[156:159], s[4:5] nt
	s_add_u32 s4, s4, 0x4000
	s_addc_u32 s5, s5, 0
	s_nop 1
	global_load_dwordx4 v[128:131], v247, s[0:1] nt
	s_add_u32 s0, s0, 0x4000
	s_addc_u32 s1, s1, 0
	global_load_dwordx4 v[132:135], v247, s[0:1] nt
	s_add_u32 s0, s0, 0x4000
	s_addc_u32 s1, s1, 0
	global_load_dwordx4 v[136:139], v247, s[0:1] nt
	s_add_u32 s0, s0, 0x4000
	s_addc_u32 s1, s1, 0
	global_load_dwordx4 v[140:143], v247, s[0:1] nt
	s_add_u32 s0, s0, 0x4000
	s_addc_u32 s1, s1, 0
	global_load_dwordx4 v[144:147], v247, s[0:1] nt
	s_add_u32 s0, s0, 0x4000
	s_addc_u32 s1, s1, 0
	global_load_dwordx4 v[148:151], v247, s[0:1] nt
	s_add_u32 s0, s0, 0x4000
	s_addc_u32 s1, s1, 0
	global_load_dwordx4 v[152:155], v247, s[0:1] nt
	s_add_u32 s0, s0, 0x4000
	s_addc_u32 s1, s1, 0
	global_load_dwordx4 v[156:159], v247, s[0:1] nt
	s_add_u32 s0, s0, 0x4000
	s_addc_u32 s1, s1, 0
	ds_read_b128 v[160:163], v246 offset:8704
	ds_read_b128 v[164:167], v246 offset:9792
	ds_read_b128 v[168:171], v246 offset:10880
	ds_read_b128 v[172:175], v246 offset:11968
	ds_read_b128 v[176:179], v246 offset:13056
	ds_read_b128 v[180:183], v246 offset:14144
	ds_read_b128 v[184:187], v246 offset:15232
	ds_read_b128 v[188:191], v246 offset:16320
	s_waitcnt vmcnt(7) lgkmcnt(7)
	v_pk_add_f32 v[128:129], v[128:129], v[160:161]
	v_pk_add_f32 v[130:131], v[130:131], v[162:163]
	global_store_dwordx4 v247, v[128:131], s[4:5] nt
	s_add_u32 s4, s4, 0x4000
	s_addc_u32 s5, s5, 0
	s_waitcnt vmcnt(7) lgkmcnt(6)
	v_pk_add_f32 v[132:133], v[132:133], v[164:165]
	v_pk_add_f32 v[134:135], v[134:135], v[166:167]
	global_store_dwordx4 v247, v[132:135], s[4:5] nt
	s_add_u32 s4, s4, 0x4000
	s_addc_u32 s5, s5, 0
	s_waitcnt vmcnt(7) lgkmcnt(5)
	v_pk_add_f32 v[136:137], v[136:137], v[168:169]
	v_pk_add_f32 v[138:139], v[138:139], v[170:171]
	global_store_dwordx4 v247, v[136:139], s[4:5] nt
	s_add_u32 s4, s4, 0x4000
	s_addc_u32 s5, s5, 0
	s_waitcnt vmcnt(7) lgkmcnt(4)
	v_pk_add_f32 v[140:141], v[140:141], v[172:173]
	v_pk_add_f32 v[142:143], v[142:143], v[174:175]
	global_store_dwordx4 v247, v[140:143], s[4:5] nt
	s_add_u32 s4, s4, 0x4000
	s_addc_u32 s5, s5, 0
	s_waitcnt vmcnt(7) lgkmcnt(3)
	v_pk_add_f32 v[144:145], v[144:145], v[176:177]
	v_pk_add_f32 v[146:147], v[146:147], v[178:179]
	global_store_dwordx4 v247, v[144:147], s[4:5] nt
	s_add_u32 s4, s4, 0x4000
	s_addc_u32 s5, s5, 0
	s_waitcnt vmcnt(7) lgkmcnt(2)
	v_pk_add_f32 v[148:149], v[148:149], v[180:181]
	v_pk_add_f32 v[150:151], v[150:151], v[182:183]
	global_store_dwordx4 v247, v[148:151], s[4:5] nt
	s_add_u32 s4, s4, 0x4000
	s_addc_u32 s5, s5, 0
	s_waitcnt vmcnt(7) lgkmcnt(1)
	v_pk_add_f32 v[152:153], v[152:153], v[184:185]
	v_pk_add_f32 v[154:155], v[154:155], v[186:187]
	global_store_dwordx4 v247, v[152:155], s[4:5] nt
	s_add_u32 s4, s4, 0x4000
	s_addc_u32 s5, s5, 0
	s_waitcnt vmcnt(7) lgkmcnt(0)
	v_pk_add_f32 v[156:157], v[156:157], v[188:189]
	v_pk_add_f32 v[158:159], v[158:159], v[190:191]
	global_store_dwordx4 v247, v[156:159], s[4:5] nt
	s_add_u32 s4, s4, 0x4000
	s_addc_u32 s5, s5, 0
	s_nop 1
	s_add_u32 s9, s9, 64
	s_branch .Lg6_tile
